# attention step: V and K fragment LDS reads issued early (after QK MFMAs / after the step barrier), half-wave max exchange via v_permlane32_swap
# speedup vs baseline: 1.0354x; 1.0011x over previous
; __device__ __forceinline__ void attn_chain(LAS unsigned char* lds, const bf16* Qb, const bf16* Kb, const bf16* Vb, bf16* Ob, float* lseb, int g0, int wave, int lane) {
;     ...
;                 float pmax = sa[0];
; #pragma unroll
;                 for (int i = 1; i < 16; ++i) pmax = fmaxf(pmax, sa[i]);
;                 pmax = fmaxf(pmax, shfl_xor_f(pmax, 32));
;                 const float mn = fmaxf(m_run, pmax), alpha = __builtin_amdgcn_exp2f(m_run - mn); m_run = mn;
;                 float ps = 0.f;
; #pragma unroll
;                 for (int i = 0; i < 16; ++i) { sa[i] = __builtin_amdgcn_exp2f(sa[i] - mn); ps += sa[i]; }
;                 l_run = l_run * alpha + ps;
; #pragma unroll
;                 for (int d = 0; d < 4; ++d)
; #pragma unroll
;                     for (int i = 0; i < 16; ++i) o[d][i] *= alpha;
;                 bf16x8 pa[2];
; #pragma unroll
;                 for (int s2 = 0; s2 < 2; ++s2) { v4u w; w.x = pk2(sa[8 * s2], sa[8 * s2 + 1]); w.y = pk2(sa[8 * s2 + 2], sa[8 * s2 + 3]); w.z = pk2(sa[8 * s2 + 4], sa[8 * s2 + 5]); w.w = pk2(sa[8 * s2 + 6], sa[8 * s2 + 7]);
;                     pa[s2] = __builtin_bit_cast(bf16x8, w); }
;                 const unsigned so_ = (unsigned)(uintptr_t)lds + (unsigned)(kk & 7) * 16384u + 8192u;
;                 s16x4 lo[2][4], hh[2][4];
; #pragma unroll
;                 for (int d = 0; d < 4; ++d) { const unsigned a0_ = trb[d][0] + so_, a1_ = trb[d][1] + so_;
;                     asm volatile("ds_read_b64_tr_b16 %0, %1" : "=&v"(lo[0][d]) : "v"(a0_) : "memory");
;                     asm volatile("ds_read_b64_tr_b16 %0, %1" : "=&v"(hh[0][d]) : "v"(a1_) : "memory");
;                     asm volatile("ds_read_b64_tr_b16 %0, %1 offset:4096" : "=&v"(lo[1][d]) : "v"(a0_) : "memory");
;                     asm volatile("ds_read_b64_tr_b16 %0, %1 offset:4096" : "=&v"(hh[1][d]) : "v"(a1_) : "memory"); }
;                 asm volatile("s_waitcnt lgkmcnt(0)" ::: "memory"); __builtin_amdgcn_sched_barrier(0);
; #pragma unroll
;                 for (int s2 = 0; s2 < 2; ++s2)
; #pragma unroll
;                     for (int d = 0; d < 4; ++d) { const bf16x8 vt = {lo[s2][d][0], lo[s2][d][1], lo[s2][d][2], lo[s2][d][3], hh[s2][d][0], hh[s2][d][1], hh[s2][d][2], hh[s2][d][3]};
;                         o[d] = __builtin_amdgcn_mfma_f32_32x32x16_bf16(vt, pa[s2], o[d], 0, 0, 0); }
.LBB0_641:
	s_add_i32 s2, s2, 0
	s_addk_i32 s2, 0x2000
	v_add_u32_e32 v214, s2, v159
	ds_read_b64_tr_b16 v[206:207], v214
	v_add_u32_e32 v215, s2, v160
	ds_read_b64_tr_b16 v[208:209], v215
	ds_read_b64_tr_b16 v[210:211], v214 offset:4096
	ds_read_b64_tr_b16 v[212:213], v215 offset:4096
	v_add_u32_e32 v214, s2, v161
	ds_read_b64_tr_b16 v[178:179], v214
	v_add_u32_e32 v215, s2, v162
	ds_read_b64_tr_b16 v[180:181], v215
	ds_read_b64_tr_b16 v[184:185], v214 offset:4096
	ds_read_b64_tr_b16 v[186:187], v215 offset:4096
	v_add_u32_e32 v214, s2, v163
	ds_read_b64_tr_b16 v[188:189], v214
	v_add_u32_e32 v215, s2, v164
	ds_read_b64_tr_b16 v[190:191], v215
	ds_read_b64_tr_b16 v[192:193], v214 offset:4096
	ds_read_b64_tr_b16 v[194:195], v215 offset:4096
	v_add_u32_e32 v214, s2, v165
	ds_read_b64_tr_b16 v[196:197], v214
	v_add_u32_e32 v215, s2, v166
	ds_read_b64_tr_b16 v[198:199], v215
	ds_read_b64_tr_b16 v[200:201], v214 offset:4096
	ds_read_b64_tr_b16 v[202:203], v215 offset:4096
	s_nop 5
	v_max_f32_e32 v170, v65, v65
	v_max_f32_e32 v171, v64, v64
	v_max_f32_e32 v170, v171, v170
	v_max3_f32 v170, v170, v66, v67
	v_max3_f32 v170, v170, v68, v69
	v_max3_f32 v170, v170, v70, v71
	v_max3_f32 v170, v170, v72, v73
	v_max3_f32 v170, v170, v74, v75
	v_max3_f32 v170, v170, v76, v77
	v_max3_f32 v170, v170, v78, v79
	v_mov_b32_e32 v171, v170
	s_nop 1
	v_permlane32_swap_b32_e32 v171, v170
	s_nop 1
	v_max3_f32 v183, v149, v170, v171
	v_sub_f32_e32 v64, v64, v183
	v_exp_f32_e32 v170, v64
	v_sub_f32_e32 v64, v65, v183
	v_exp_f32_e32 v65, v64
	v_sub_f32_e32 v64, v66, v183
	v_exp_f32_e32 v171, v64
	v_sub_f32_e32 v64, v67, v183
	v_sub_f32_e32 v66, v78, v183
	v_exp_f32_e32 v67, v64
	v_sub_f32_e32 v64, v68, v183
	v_exp_f32_e32 v78, v66
	v_sub_f32_e32 v66, v79, v183
	v_exp_f32_e32 v68, v64
	v_sub_f32_e32 v64, v69, v183
	v_exp_f32_e32 v79, v66
	v_add_f32_e32 v66, 0, v170
	v_exp_f32_e32 v69, v64
	v_sub_f32_e32 v64, v70, v183
	v_add_f32_e32 v66, v65, v66
	v_exp_f32_e32 v70, v64
	v_sub_f32_e32 v64, v71, v183
	v_add_f32_e32 v66, v171, v66
	v_exp_f32_e32 v71, v64
	v_sub_f32_e32 v64, v72, v183
	v_add_f32_e32 v66, v67, v66
	v_exp_f32_e32 v72, v64
	v_sub_f32_e32 v64, v73, v183
	v_add_f32_e32 v66, v68, v66
	v_exp_f32_e32 v73, v64
	v_sub_f32_e32 v64, v74, v183
	v_add_f32_e32 v66, v69, v66
	v_exp_f32_e32 v74, v64
	v_sub_f32_e32 v64, v75, v183
	v_add_f32_e32 v66, v70, v66
	v_exp_f32_e32 v75, v64
	v_sub_f32_e32 v64, v76, v183
	v_add_f32_e32 v66, v71, v66
	v_exp_f32_e32 v76, v64
	v_sub_f32_e32 v64, v77, v183
	v_add_f32_e32 v66, v72, v66
	v_exp_f32_e32 v77, v64
	v_add_f32_e32 v66, v73, v66
	v_sub_f32_e32 v149, v149, v183
	v_add_f32_e32 v66, v74, v66
	v_exp_f32_e32 v64, v149
	v_add_f32_e32 v66, v75, v66
	v_add_f32_e32 v66, v76, v66
	v_add_f32_e32 v66, v77, v66
	v_add_f32_e32 v66, v78, v66
	v_pk_mul_f32 v[62:63], v[62:63], v[64:65] op_sel_hi:[1,0]
	v_pk_mul_f32 v[60:61], v[60:61], v[64:65] op_sel_hi:[1,0]
	v_pk_mul_f32 v[58:59], v[58:59], v[64:65] op_sel_hi:[1,0]
	v_pk_mul_f32 v[56:57], v[56:57], v[64:65] op_sel_hi:[1,0]
	v_pk_mul_f32 v[54:55], v[54:55], v[64:65] op_sel_hi:[1,0]
	v_pk_mul_f32 v[52:53], v[52:53], v[64:65] op_sel_hi:[1,0]
	v_pk_mul_f32 v[50:51], v[50:51], v[64:65] op_sel_hi:[1,0]
	v_pk_mul_f32 v[48:49], v[48:49], v[64:65] op_sel_hi:[1,0]
	v_pk_mul_f32 v[46:47], v[46:47], v[64:65] op_sel_hi:[1,0]
	v_pk_mul_f32 v[44:45], v[44:45], v[64:65] op_sel_hi:[1,0]
	v_pk_mul_f32 v[42:43], v[42:43], v[64:65] op_sel_hi:[1,0]
	v_pk_mul_f32 v[40:41], v[40:41], v[64:65] op_sel_hi:[1,0]
	v_pk_mul_f32 v[38:39], v[38:39], v[64:65] op_sel_hi:[1,0]
	v_pk_mul_f32 v[36:37], v[36:37], v[64:65] op_sel_hi:[1,0]
	v_pk_mul_f32 v[34:35], v[34:35], v[64:65] op_sel_hi:[1,0]
	v_pk_mul_f32 v[32:33], v[32:33], v[64:65] op_sel_hi:[1,0]
	v_pk_mul_f32 v[30:31], v[30:31], v[64:65] op_sel_hi:[1,0]
	v_pk_mul_f32 v[28:29], v[28:29], v[64:65] op_sel_hi:[1,0]
	v_pk_mul_f32 v[26:27], v[26:27], v[64:65] op_sel_hi:[1,0]
	v_pk_mul_f32 v[24:25], v[24:25], v[64:65] op_sel_hi:[1,0]
	v_pk_mul_f32 v[22:23], v[22:23], v[64:65] op_sel_hi:[1,0]
	v_pk_mul_f32 v[20:21], v[20:21], v[64:65] op_sel_hi:[1,0]
	v_pk_mul_f32 v[18:19], v[18:19], v[64:65] op_sel_hi:[1,0]
	v_pk_mul_f32 v[16:17], v[16:17], v[64:65] op_sel_hi:[1,0]
	v_pk_mul_f32 v[14:15], v[14:15], v[64:65] op_sel_hi:[1,0]
	v_pk_mul_f32 v[12:13], v[12:13], v[64:65] op_sel_hi:[1,0]
	v_pk_mul_f32 v[10:11], v[10:11], v[64:65] op_sel_hi:[1,0]
	v_pk_mul_f32 v[8:9], v[8:9], v[64:65] op_sel_hi:[1,0]
	v_pk_mul_f32 v[6:7], v[6:7], v[64:65] op_sel_hi:[1,0]
	v_pk_mul_f32 v[4:5], v[4:5], v[64:65] op_sel_hi:[1,0]
	v_pk_mul_f32 v[2:3], v[2:3], v[64:65] op_sel_hi:[1,0]
	v_pk_mul_f32 v[0:1], v[0:1], v[64:65] op_sel_hi:[1,0]
	v_add_f32_e32 v204, v79, v66
	v_cvt_pk_bf16_f32 v66, v170, v65
	v_cvt_pk_bf16_f32 v68, v68, v69
	v_cvt_pk_bf16_f32 v69, v70, v71
	v_cvt_pk_bf16_f32 v71, v74, v75
	v_cvt_pk_bf16_f32 v70, v72, v73
	v_cvt_pk_bf16_f32 v72, v76, v77
	v_cvt_pk_bf16_f32 v73, v78, v79
	v_cvt_pk_bf16_f32 v67, v171, v67
	s_nop 1
	s_waitcnt lgkmcnt(0)
	v_mfma_f32_32x32x16_bf16 v[48:63], v[206:209], v[66:69], v[48:63]
	v_fmac_f32_e32 v204, v182, v64
	v_mov_b32_e32 v149, v183
	v_mov_b32_e32 v182, v204
	v_mfma_f32_32x32x16_bf16 v[32:47], v[178:181], v[66:69], v[32:47]
	v_mfma_f32_32x32x16_bf16 v[16:31], v[188:191], v[66:69], v[16:31]
	v_mfma_f32_32x32x16_bf16 v[0:15], v[196:199], v[66:69], v[0:15]
	v_mfma_f32_32x32x16_bf16 v[48:63], v[210:213], v[70:73], v[48:63]
	v_mfma_f32_32x32x16_bf16 v[32:47], v[184:187], v[70:73], v[32:47]
	v_mfma_f32_32x32x16_bf16 v[16:31], v[192:195], v[70:73], v[16:31]
	v_mfma_f32_32x32x16_bf16 v[0:15], v[200:203], v[70:73], v[0:15]

; #define LAS __attribute__((address_space(3)))
; #define AC_QLOAD(n_) do { const int gq_ = g0 + wave + 8 * (n_); AC_MAP(gq_, pq_, dq_, rq_, lq_); \
;     const bf16* qp_ = Qb + (size_t)(rq_ + dq_ * (32 * lq_ + r32)) * 1024 + 64 * hi; \
;     _Pragma("unroll") for (int s_ = 0; s_ < 8; ++s_) asm volatile("global_load_dwordx4 %0, %1, off" : "=v"(qn[s_]) : "v"(qp_ + 8 * s_) : "memory"); } while (0)
; __device__ __forceinline__ void attn_chain(LAS unsigned char* lds, const bf16* Qb, const bf16* Kb, const bf16* Vb, bf16* Ob, float* lseb, int g0, int wave, int lane) {
;     ...
;         __builtin_amdgcn_s_barrier();
;         asm volatile("" ::: "memory");
;         { int k0, k1 = -1;
;           if (ph == 0) k0 = 8 * mm + 4; else if (ph == 1) { k0 = 8 * mm + 5; k1 = k0 + 1; } else if (ph == 2) k0 = 8 * mm + 7; else if (ph == 3) { k0 = 8 * mm + 8; k1 = k0 + 1; } else { k0 = 8 * mm + 10; k1 = k0 + 1; }
;           p1 = 0;
;           if (k0 < NKB) { AC_ISSUE(k0); p1 = 2; }
;           if (k1 >= 0 && k1 < NKB) { AC_ISSUE(k1); p1 += 2; } }
;         if (++ph == 5) { ph = 0; ++mm; }
;         if (act && t == 3 && n + 1 < NJOB) AC_QLOAD(n + 1);
;         if (act) {
;             if (t == 0 && n > 0) AC_FINALIZE(n - 1);
;             const int L = wave + 8 * n, kk = L + t, gq = g0 + L, gk = gq - 2 + t;
;             AC_MAP(gq, pq, dq, rq, lq);
;             const bool valid = gk >= 0 && gk < 384 && (gk >> 7) == pq && (((gk & 127) >> shpq) == rq);
;             (void)dq; (void)lq;
;             if (valid) {
;                 const unsigned kb_ = kbl + (unsigned)(kk & 7) * 16384u;
;                 bf16x8 kf[8];
; #pragma unroll
;                 for (int s2 = 0; s2 < 8; ++s2) kf[s2] = *(const LAS bf16x8*)(lds + (kb_ ^ ((unsigned)s2 << 4)));
.LBB0_671:
	s_barrier
	s_mul_i32 s100, s14, 0xfffec000
	s_add_i32 s100, s82, s100
	s_and_b32 s100, s100, 0x1c000
	v_add_u32_e32 v216, s100, v158
	v_xad_u32 v217, v216, 16, 0
	ds_read_b128 v[220:223], v216
	ds_read_b128 v[170:173], v217
	v_xad_u32 v217, v216, 32, 0
	v_xad_u32 v218, v216, 48, 0
	ds_read_b128 v[178:181], v217
	ds_read_b128 v[184:187], v218
	v_xad_u32 v217, v216, 64, 0
	v_xor_b32_e32 v218, 0x50, v216
	ds_read_b128 v[188:191], v217
	ds_read_b128 v[192:195], v218
	v_xor_b32_e32 v217, 0x60, v216
	v_xor_b32_e32 v218, 0x70, v216
	ds_read_b128 v[196:199], v217
	ds_read_b128 v[200:203], v218
	s_lshl_b32 s42, s85, 3
	s_mov_b64 s[78:79], -1
	s_mov_b64 s[74:75], 0
	s_cmp_lt_i32 s86, 2
	s_mov_b64 s[76:77], 0
	s_cbranch_scc1 .LBB0_677
	s_cmp_gt_i32 s86, 2
	s_cbranch_scc0 .LBB0_682
	s_cmp_eq_u32 s86, 3
	s_mov_b64 s[76:77], -1
	s_cbranch_scc0 .LBB0_675
	s_add_i32 s40, s42, 8
	s_add_i32 s33, s42, 9
	s_mov_b64 s[76:77], 0

; #define LAS __attribute__((address_space(3)))
; __device__ __forceinline__ void attn_chain(LAS unsigned char* lds, const bf16* Qb, const bf16* Kb, const bf16* Vb, bf16* Ob, float* lseb, int g0, int wave, int lane) {
;     ...
;             const int L = wave + 8 * n, kk = L + t, gq = g0 + L, gk = gq - 2 + t;
;             AC_MAP(gq, pq, dq, rq, lq);
;             const bool valid = gk >= 0 && gk < 384 && (gk >> 7) == pq && (((gk & 127) >> shpq) == rq);
;             (void)dq; (void)lq;
;             if (valid) {
;                 const unsigned kb_ = kbl + (unsigned)(kk & 7) * 16384u;
;                 bf16x8 kf[8];
; #pragma unroll
;                 for (int s2 = 0; s2 < 8; ++s2) kf[s2] = *(const LAS bf16x8*)(lds + (kb_ ^ ((unsigned)s2 << 4)));
;                 f32x16 sa;
; #pragma unroll
;                 for (int i = 0; i < 16; ++i) sa[i] = 0.f;
;                 __builtin_amdgcn_sched_barrier(0); asm volatile("s_waitcnt lgkmcnt(0)" ::: "memory"); __builtin_amdgcn_sched_barrier(0);
; #pragma unroll
;                 for (int s2 = 0; s2 < 8; ++s2) sa = __builtin_amdgcn_mfma_f32_32x32x16_bf16(kf[s2], qf[s2], sa, 0, 0, 0);
.LBB0_696:
	s_and_b32 s3, s83, 0xff
	s_mul_hi_u32 s3, s3, 0x33333334
	s_lshl_b32 s3, s3, 3
	s_add_i32 s3, s59, s3
	s_add_i32 s2, s2, s66
	s_add_i32 s30, s30, s3
	s_lshr_b32 s3, s2, 7
	s_cmpk_gt_u32 s30, 0x17f
	s_cselect_b64 s[6:7], -1, 0
	s_lshr_b32 s12, s30, 7
	s_cmp_lg_u32 s12, s3
	s_cselect_b64 s[12:13], -1, 0
	s_or_b64 s[6:7], s[6:7], s[12:13]
	s_and_b64 vcc, exec, s[6:7]
	s_cbranch_vccnz .LBB0_642
	s_lshl_b32 s3, s3, 1
	s_and_b32 s2, s2, 0x7f
	s_sub_i32 s3, 7, s3
	s_and_b32 s6, s30, 0x7f
	s_lshr_b32 s2, s2, s3
	s_lshr_b32 s3, s6, s3
	s_cmp_lg_u32 s3, s2
	s_cbranch_scc1 .LBB0_642
	s_mul_i32 s2, s14, 0xfffec000
	s_add_i32 s2, s82, s2
	s_and_b32 s2, s2, 0x1c000
	s_waitcnt lgkmcnt(0)
	s_waitcnt lgkmcnt(0)
	v_mfma_f32_32x32x16_bf16 v[64:79], v[220:223], v[112:115], 0
	s_cmp_lt_i32 s15, 4
	v_mfma_f32_32x32x16_bf16 v[64:79], v[170:173], v[116:119], v[64:79]
	v_mfma_f32_32x32x16_bf16 v[64:79], v[178:181], v[120:123], v[64:79]
	v_mfma_f32_32x32x16_bf16 v[64:79], v[184:187], v[124:127], v[64:79]
	v_mfma_f32_32x32x16_bf16 v[64:79], v[188:191], v[128:131], v[64:79]
	v_mfma_f32_32x32x16_bf16 v[64:79], v[192:195], v[132:135], v[64:79]
	v_mfma_f32_32x32x16_bf16 v[64:79], v[196:199], v[136:139], v[64:79]
	v_mfma_f32_32x32x16_bf16 v[64:79], v[200:203], v[140:143], v[64:79]
	s_cbranch_scc1 .LBB0_708
	s_cmp_eq_u32 s15, 4
	s_cselect_b64 s[6:7], -1, 0
	s_cbranch_execz .LBB0_709
	s_branch .LBB0_710
